# RG-LRU conv loop: loads of three channel blocks in flight (de-serialised), on top of resid2 out-proj L1
# speedup vs baseline: 1.0534x; 1.0029x over previous
.LBB0_304:
	s_mov_b64 s[8:9], s[0:1]
	v_mov_b32_e32 v32, v154
	v_mov_b32_e32 v41, v154
	v_mov_b32_e32 v40, v154
	s_load_dwordx4 s[4:7], s[8:9], 0x48
	s_load_dwordx2 s[10:11], s[8:9], 0x38
	v_ashrrev_i32_e32 v33, 31, v32
	v_lshlrev_b64 v[0:1], 2, v[32:33]
	v_and_b32_e32 v33, 7, v32
	s_waitcnt lgkmcnt(0)
	v_lshl_add_u64 v[2:3], s[6:7], 0, v[0:1]
	global_load_dword v10, v[2:3], off
	v_lshl_add_u64 v[2:3], s[10:11], 0, v[0:1]
	v_lshl_add_u64 v[0:1], s[4:5], 0, v[0:1]
	global_load_dword v11, v[2:3], off
	global_load_dword v12, v[0:1], off
	s_load_dwordx2 s[44:45], s[8:9], 0x138
	s_load_dwordx4 s[12:15], s[8:9], 0x20
	v_lshl_add_u32 v0, v32, 2, 0
	v_mov_b32_e32 v1, v49
	v_add_u32_e32 v13, 0x19600, v0
	v_add_u32_e32 v14, 0x19e00, v0
	v_add_u32_e32 v15, 0x1a600, v0
	v_lshlrev_b32_e32 v0, 5, v33
	s_waitcnt lgkmcnt(0)
	v_lshl_add_u64 v[16:17], s[14:15], 0, v[0:1]
	v_lshl_add_u64 v[18:19], s[12:13], 0, v[0:1]
	s_lshl_b32 s18, s3, 6
	s_and_b32 s4, s18, 0x7c0
	v_ashrrev_i32_e32 v42, 3, v32
	s_and_b32 s6, s18, 0xfffff800
	v_add_u32_e32 v2, s4, v42
	v_cmp_lt_i32_e64 s[4:5], 2, v2
	v_add_u32_e32 v20, s6, v2
	v_cmp_lt_i32_e64 s[6:7], 1, v2
	v_cmp_lt_i32_e64 s[8:9], 0, v2
	v_cmp_lt_i32_e64 s[10:11], -1, v2
	v_mov_b64_e32 v[2:3], s[44:45]
	v_add_u32_e32 v26, -3, v20
	v_add_u32_e32 v24, -2, v20
	v_add_u32_e32 v22, -1, v20
	v_mad_i64_i32 v[20:21], s[12:13], v20, s57, v[2:3]
	v_mul_lo_u32 v60, v42, s56
	v_lshlrev_b32_e32 v48, 4, v33
	v_add3_u32 v61, v60, v48, 0
	v_mov_b64_e32 v[4:5], s[44:45]
	v_mov_b64_e32 v[6:7], s[44:45]
	v_mov_b64_e32 v[8:9], s[44:45]
	s_mov_b64 s[16:17], 0
	v_mad_i64_i32 v[22:23], s[12:13], v22, s57, v[4:5]
	v_mad_i64_i32 v[24:25], s[12:13], v24, s57, v[6:7]
	v_mad_i64_i32 v[26:27], s[12:13], v26, s57, v[8:9]
	v_mov_b32_e32 v43, v61
	s_waitcnt vmcnt(2)
	v_mul_f32_e64 v0, |v10|, s52
	v_exp_f32_e32 v0, v0
	v_max_f32_e32 v1, v10, v10
	v_min_f32_e32 v1, 0, v1
	s_waitcnt vmcnt(1)
	ds_write_b32 v14, v11
	v_add_f32_e32 v0, 1.0, v0
	v_cmp_gt_f32_e32 vcc, s53, v0
	s_waitcnt vmcnt(0)
	ds_write_b32 v15, v12
	v_cndmask_b32_e64 v2, 0, 32, vcc
	v_ldexp_f32 v0, v0, v2
	v_log_f32_e32 v0, v0
	v_cndmask_b32_e32 v2, 0, v51, vcc
	v_mul_f32_e32 v3, 0x3f317217, v0
	v_fma_f32 v3, v0, s54, -v3
	v_fmac_f32_e32 v3, 0x3377d1cf, v0
	v_fmac_f32_e32 v3, 0x3f317217, v0
	v_cmp_lt_f32_e64 vcc, |v0|, s55
	s_nop 1
	v_cndmask_b32_e32 v0, v0, v3, vcc
	v_sub_f32_e32 v0, v0, v2
	v_sub_f32_e32 v0, v1, v0
	ds_write_b32 v13, v0
	s_load_dwordx4 s[96:99], s[0:1], 0x20
	s_add_u32 s94, s44, 0x4300000
	s_addc_u32 s95, s45, 0
	v_add_u32_e32 v244, s18, v42
	v_add_u32_e32 v244, -3, v244
	v_add_u32_e32 v245, 1, v244
	v_add_u32_e32 v246, 2, v244
	v_add_u32_e32 v247, 3, v244
	v_max_i32_e32 v244, 0, v244
	v_max_i32_e32 v245, 0, v245
	v_max_i32_e32 v246, 0, v246
	v_max_i32_e32 v247, 0, v247
	v_mul_lo_u32 v244, v244, s57
	v_mul_lo_u32 v245, v245, s57
	v_mul_lo_u32 v246, v246, s57
	v_mul_lo_u32 v247, v247, s57
	v_add_u32_e32 v244, v244, v48
	v_add_u32_e32 v245, v245, v48
	v_add_u32_e32 v246, v246, v48
	v_add_u32_e32 v247, v247, v48
	v_lshlrev_b32_e32 v248, 5, v33
	v_add_u32_e32 v249, 0x1000, v248
	v_mov_b32_e32 v62, v61
	s_waitcnt lgkmcnt(0)
	global_load_dwordx4 v[64:67], v244, s[94:95]
	global_load_dwordx4 v[68:71], v245, s[94:95]
	global_load_dwordx4 v[72:75], v246, s[94:95]
	global_load_dwordx4 v[76:79], v247, s[94:95]
	global_load_dwordx4 v[80:83], v248, s[96:97]
	global_load_dwordx4 v[84:87], v248, s[96:97] offset:16
	global_load_dwordx4 v[88:91], v248, s[96:97] offset:2048
	global_load_dwordx4 v[92:95], v248, s[96:97] offset:2064
	global_load_dwordx4 v[96:99], v249, s[96:97]
	global_load_dwordx4 v[100:103], v249, s[96:97] offset:16
	global_load_dwordx4 v[104:107], v249, s[96:97] offset:2048
	global_load_dwordx4 v[108:111], v249, s[96:97] offset:2064
	global_load_dwordx4 v[112:115], v248, s[98:99]
	global_load_dwordx4 v[116:119], v248, s[98:99] offset:16
	global_load_dwordx4 v[156:159], v244, s[94:95] offset:128
	global_load_dwordx4 v[160:163], v245, s[94:95] offset:128
	global_load_dwordx4 v[164:167], v246, s[94:95] offset:128
	global_load_dwordx4 v[168:171], v247, s[94:95] offset:128
	global_load_dwordx4 v[172:175], v248, s[96:97] offset:256
	global_load_dwordx4 v[176:179], v248, s[96:97] offset:272
	global_load_dwordx4 v[180:183], v248, s[96:97] offset:2304
	global_load_dwordx4 v[184:187], v248, s[96:97] offset:2320
	global_load_dwordx4 v[188:191], v249, s[96:97] offset:256
	global_load_dwordx4 v[192:195], v249, s[96:97] offset:272
	global_load_dwordx4 v[196:199], v249, s[96:97] offset:2304
	global_load_dwordx4 v[200:203], v249, s[96:97] offset:2320
	global_load_dwordx4 v[204:207], v248, s[98:99] offset:256
	global_load_dwordx4 v[208:211], v248, s[98:99] offset:272
	global_load_dwordx4 v[120:123], v244, s[94:95] offset:256
	global_load_dwordx4 v[124:127], v245, s[94:95] offset:256
	global_load_dwordx4 v[128:131], v246, s[94:95] offset:256
	global_load_dwordx4 v[132:135], v247, s[94:95] offset:256
	global_load_dwordx4 v[136:139], v248, s[96:97] offset:512
	global_load_dwordx4 v[140:143], v248, s[96:97] offset:528
	global_load_dwordx4 v[144:147], v248, s[96:97] offset:2560
	global_load_dwordx4 v[148:151], v248, s[96:97] offset:2576
	global_load_dwordx4 v[212:215], v249, s[96:97] offset:512
	global_load_dwordx4 v[216:219], v249, s[96:97] offset:528
	global_load_dwordx4 v[220:223], v249, s[96:97] offset:2560
	global_load_dwordx4 v[224:227], v249, s[96:97] offset:2576
	global_load_dwordx4 v[228:231], v248, s[98:99] offset:512
	global_load_dwordx4 v[232:235], v248, s[98:99] offset:528
	s_waitcnt vmcnt(28)
	v_lshlrev_b32_e32 v236, 16, v64
	v_and_b32_e32 v237, 0xffff0000, v64
	v_lshlrev_b32_e32 v238, 16, v65
	v_and_b32_e32 v239, 0xffff0000, v65
	v_lshlrev_b32_e32 v240, 16, v66
	v_and_b32_e32 v241, 0xffff0000, v66
	v_lshlrev_b32_e32 v242, 16, v67
	v_and_b32_e32 v243, 0xffff0000, v67
	s_and_saveexec_b64 s[100:101], s[4:5]
	v_pk_fma_f32 v[114:115], v[82:83], v[238:239], v[114:115]
	v_pk_fma_f32 v[112:113], v[80:81], v[236:237], v[112:113]
	v_pk_fma_f32 v[118:119], v[86:87], v[242:243], v[118:119]
	v_pk_fma_f32 v[116:117], v[84:85], v[240:241], v[116:117]
	s_mov_b64 exec, s[100:101]
	v_lshlrev_b32_e32 v236, 16, v68
	v_and_b32_e32 v237, 0xffff0000, v68
	v_lshlrev_b32_e32 v238, 16, v69
	v_and_b32_e32 v239, 0xffff0000, v69
	v_lshlrev_b32_e32 v240, 16, v70
	v_and_b32_e32 v241, 0xffff0000, v70
	v_lshlrev_b32_e32 v242, 16, v71
	v_and_b32_e32 v243, 0xffff0000, v71
	s_and_saveexec_b64 s[100:101], s[6:7]
	v_pk_fma_f32 v[114:115], v[90:91], v[238:239], v[114:115]
	v_pk_fma_f32 v[112:113], v[88:89], v[236:237], v[112:113]
	v_pk_fma_f32 v[118:119], v[94:95], v[242:243], v[118:119]
	v_pk_fma_f32 v[116:117], v[92:93], v[240:241], v[116:117]
	s_mov_b64 exec, s[100:101]
	v_lshlrev_b32_e32 v236, 16, v72
	v_and_b32_e32 v237, 0xffff0000, v72
	v_lshlrev_b32_e32 v238, 16, v73
	v_and_b32_e32 v239, 0xffff0000, v73
	v_lshlrev_b32_e32 v240, 16, v74
	v_and_b32_e32 v241, 0xffff0000, v74
	v_lshlrev_b32_e32 v242, 16, v75
	v_and_b32_e32 v243, 0xffff0000, v75
	s_and_saveexec_b64 s[100:101], s[8:9]
	v_pk_fma_f32 v[114:115], v[98:99], v[238:239], v[114:115]
	v_pk_fma_f32 v[112:113], v[96:97], v[236:237], v[112:113]
	v_pk_fma_f32 v[118:119], v[102:103], v[242:243], v[118:119]
	v_pk_fma_f32 v[116:117], v[100:101], v[240:241], v[116:117]
	s_mov_b64 exec, s[100:101]
	v_lshlrev_b32_e32 v236, 16, v76
	v_and_b32_e32 v237, 0xffff0000, v76
	v_lshlrev_b32_e32 v238, 16, v77
	v_and_b32_e32 v239, 0xffff0000, v77
	v_lshlrev_b32_e32 v240, 16, v78
	v_and_b32_e32 v241, 0xffff0000, v78
	v_lshlrev_b32_e32 v242, 16, v79
	v_and_b32_e32 v243, 0xffff0000, v79
	v_pk_fma_f32 v[114:115], v[106:107], v[238:239], v[114:115]
	v_pk_fma_f32 v[112:113], v[104:105], v[236:237], v[112:113]
	v_pk_fma_f32 v[118:119], v[110:111], v[242:243], v[118:119]
	v_pk_fma_f32 v[116:117], v[108:109], v[240:241], v[116:117]
	v_cvt_pk_bf16_f32 v250, v112, v113
	v_cvt_pk_bf16_f32 v251, v114, v115
	v_cvt_pk_bf16_f32 v252, v116, v117
	v_cvt_pk_bf16_f32 v253, v118, v119
	ds_write_b128 v62, v[250:253]
	global_load_dwordx4 v[64:67], v244, s[94:95] offset:384
	global_load_dwordx4 v[68:71], v245, s[94:95] offset:384
	global_load_dwordx4 v[72:75], v246, s[94:95] offset:384
	global_load_dwordx4 v[76:79], v247, s[94:95] offset:384
	global_load_dwordx4 v[80:83], v248, s[96:97] offset:768
	global_load_dwordx4 v[84:87], v248, s[96:97] offset:784
	global_load_dwordx4 v[88:91], v248, s[96:97] offset:2816
	global_load_dwordx4 v[92:95], v248, s[96:97] offset:2832
	global_load_dwordx4 v[96:99], v249, s[96:97] offset:768
	global_load_dwordx4 v[100:103], v249, s[96:97] offset:784
	global_load_dwordx4 v[104:107], v249, s[96:97] offset:2816
	global_load_dwordx4 v[108:111], v249, s[96:97] offset:2832
	global_load_dwordx4 v[112:115], v248, s[98:99] offset:768
	global_load_dwordx4 v[116:119], v248, s[98:99] offset:784
	s_waitcnt vmcnt(28)
	v_lshlrev_b32_e32 v236, 16, v156
	v_and_b32_e32 v237, 0xffff0000, v156
	v_lshlrev_b32_e32 v238, 16, v157
	v_and_b32_e32 v239, 0xffff0000, v157
	v_lshlrev_b32_e32 v240, 16, v158
	v_and_b32_e32 v241, 0xffff0000, v158
	v_lshlrev_b32_e32 v242, 16, v159
	v_and_b32_e32 v243, 0xffff0000, v159
	s_and_saveexec_b64 s[100:101], s[4:5]
	v_pk_fma_f32 v[206:207], v[174:175], v[238:239], v[206:207]
	v_pk_fma_f32 v[204:205], v[172:173], v[236:237], v[204:205]
	v_pk_fma_f32 v[210:211], v[178:179], v[242:243], v[210:211]
	v_pk_fma_f32 v[208:209], v[176:177], v[240:241], v[208:209]
	s_mov_b64 exec, s[100:101]
	v_lshlrev_b32_e32 v236, 16, v160
	v_and_b32_e32 v237, 0xffff0000, v160
	v_lshlrev_b32_e32 v238, 16, v161
	v_and_b32_e32 v239, 0xffff0000, v161
	v_lshlrev_b32_e32 v240, 16, v162
	v_and_b32_e32 v241, 0xffff0000, v162
	v_lshlrev_b32_e32 v242, 16, v163
	v_and_b32_e32 v243, 0xffff0000, v163
	s_and_saveexec_b64 s[100:101], s[6:7]
	v_pk_fma_f32 v[206:207], v[182:183], v[238:239], v[206:207]
	v_pk_fma_f32 v[204:205], v[180:181], v[236:237], v[204:205]
	v_pk_fma_f32 v[210:211], v[186:187], v[242:243], v[210:211]
	v_pk_fma_f32 v[208:209], v[184:185], v[240:241], v[208:209]
	s_mov_b64 exec, s[100:101]
	v_lshlrev_b32_e32 v236, 16, v164
	v_and_b32_e32 v237, 0xffff0000, v164
	v_lshlrev_b32_e32 v238, 16, v165
	v_and_b32_e32 v239, 0xffff0000, v165
	v_lshlrev_b32_e32 v240, 16, v166
	v_and_b32_e32 v241, 0xffff0000, v166
	v_lshlrev_b32_e32 v242, 16, v167
	v_and_b32_e32 v243, 0xffff0000, v167
	s_and_saveexec_b64 s[100:101], s[8:9]
	v_pk_fma_f32 v[206:207], v[190:191], v[238:239], v[206:207]
	v_pk_fma_f32 v[204:205], v[188:189], v[236:237], v[204:205]
	v_pk_fma_f32 v[210:211], v[194:195], v[242:243], v[210:211]
	v_pk_fma_f32 v[208:209], v[192:193], v[240:241], v[208:209]
	s_mov_b64 exec, s[100:101]
	v_lshlrev_b32_e32 v236, 16, v168
	v_and_b32_e32 v237, 0xffff0000, v168
	v_lshlrev_b32_e32 v238, 16, v169
	v_and_b32_e32 v239, 0xffff0000, v169
	v_lshlrev_b32_e32 v240, 16, v170
	v_and_b32_e32 v241, 0xffff0000, v170
	v_lshlrev_b32_e32 v242, 16, v171
	v_and_b32_e32 v243, 0xffff0000, v171
	v_pk_fma_f32 v[206:207], v[198:199], v[238:239], v[206:207]
	v_pk_fma_f32 v[204:205], v[196:197], v[236:237], v[204:205]
	v_pk_fma_f32 v[210:211], v[202:203], v[242:243], v[210:211]
	v_pk_fma_f32 v[208:209], v[200:201], v[240:241], v[208:209]
	v_cvt_pk_bf16_f32 v250, v204, v205
	v_cvt_pk_bf16_f32 v251, v206, v207
	v_cvt_pk_bf16_f32 v252, v208, v209
	v_cvt_pk_bf16_f32 v253, v210, v211
	ds_write_b128 v62, v[250:253] offset:128
	global_load_dwordx4 v[156:159], v244, s[94:95] offset:512
	global_load_dwordx4 v[160:163], v245, s[94:95] offset:512
	global_load_dwordx4 v[164:167], v246, s[94:95] offset:512
	global_load_dwordx4 v[168:171], v247, s[94:95] offset:512
	global_load_dwordx4 v[172:175], v248, s[96:97] offset:1024
	global_load_dwordx4 v[176:179], v248, s[96:97] offset:1040
	global_load_dwordx4 v[180:183], v248, s[96:97] offset:3072
	global_load_dwordx4 v[184:187], v248, s[96:97] offset:3088
	global_load_dwordx4 v[188:191], v249, s[96:97] offset:1024
	global_load_dwordx4 v[192:195], v249, s[96:97] offset:1040
	global_load_dwordx4 v[196:199], v249, s[96:97] offset:3072
	global_load_dwordx4 v[200:203], v249, s[96:97] offset:3088
	global_load_dwordx4 v[204:207], v248, s[98:99] offset:1024
	global_load_dwordx4 v[208:211], v248, s[98:99] offset:1040
	s_waitcnt vmcnt(28)
	v_lshlrev_b32_e32 v236, 16, v120
	v_and_b32_e32 v237, 0xffff0000, v120
	v_lshlrev_b32_e32 v238, 16, v121
	v_and_b32_e32 v239, 0xffff0000, v121
	v_lshlrev_b32_e32 v240, 16, v122
	v_and_b32_e32 v241, 0xffff0000, v122
	v_lshlrev_b32_e32 v242, 16, v123
	v_and_b32_e32 v243, 0xffff0000, v123
	s_and_saveexec_b64 s[100:101], s[4:5]
	v_pk_fma_f32 v[230:231], v[138:139], v[238:239], v[230:231]
	v_pk_fma_f32 v[228:229], v[136:137], v[236:237], v[228:229]
	v_pk_fma_f32 v[234:235], v[142:143], v[242:243], v[234:235]
	v_pk_fma_f32 v[232:233], v[140:141], v[240:241], v[232:233]
	s_mov_b64 exec, s[100:101]
	v_lshlrev_b32_e32 v236, 16, v124
	v_and_b32_e32 v237, 0xffff0000, v124
	v_lshlrev_b32_e32 v238, 16, v125
	v_and_b32_e32 v239, 0xffff0000, v125
	v_lshlrev_b32_e32 v240, 16, v126
	v_and_b32_e32 v241, 0xffff0000, v126
	v_lshlrev_b32_e32 v242, 16, v127
	v_and_b32_e32 v243, 0xffff0000, v127
	s_and_saveexec_b64 s[100:101], s[6:7]
	v_pk_fma_f32 v[230:231], v[146:147], v[238:239], v[230:231]
	v_pk_fma_f32 v[228:229], v[144:145], v[236:237], v[228:229]
	v_pk_fma_f32 v[234:235], v[150:151], v[242:243], v[234:235]
	v_pk_fma_f32 v[232:233], v[148:149], v[240:241], v[232:233]
	s_mov_b64 exec, s[100:101]
	v_lshlrev_b32_e32 v236, 16, v128
	v_and_b32_e32 v237, 0xffff0000, v128
	v_lshlrev_b32_e32 v238, 16, v129
	v_and_b32_e32 v239, 0xffff0000, v129
	v_lshlrev_b32_e32 v240, 16, v130
	v_and_b32_e32 v241, 0xffff0000, v130
	v_lshlrev_b32_e32 v242, 16, v131
	v_and_b32_e32 v243, 0xffff0000, v131
	s_and_saveexec_b64 s[100:101], s[8:9]
	v_pk_fma_f32 v[230:231], v[214:215], v[238:239], v[230:231]
	v_pk_fma_f32 v[228:229], v[212:213], v[236:237], v[228:229]
	v_pk_fma_f32 v[234:235], v[218:219], v[242:243], v[234:235]
	v_pk_fma_f32 v[232:233], v[216:217], v[240:241], v[232:233]
	s_mov_b64 exec, s[100:101]
	v_lshlrev_b32_e32 v236, 16, v132
	v_and_b32_e32 v237, 0xffff0000, v132
	v_lshlrev_b32_e32 v238, 16, v133
	v_and_b32_e32 v239, 0xffff0000, v133
	v_lshlrev_b32_e32 v240, 16, v134
	v_and_b32_e32 v241, 0xffff0000, v134
	v_lshlrev_b32_e32 v242, 16, v135
	v_and_b32_e32 v243, 0xffff0000, v135
	v_pk_fma_f32 v[230:231], v[222:223], v[238:239], v[230:231]
	v_pk_fma_f32 v[228:229], v[220:221], v[236:237], v[228:229]
	v_pk_fma_f32 v[234:235], v[226:227], v[242:243], v[234:235]
	v_pk_fma_f32 v[232:233], v[224:225], v[240:241], v[232:233]
	v_cvt_pk_bf16_f32 v250, v228, v229
	v_cvt_pk_bf16_f32 v251, v230, v231
	v_cvt_pk_bf16_f32 v252, v232, v233
	v_cvt_pk_bf16_f32 v253, v234, v235
	ds_write_b128 v62, v[250:253] offset:256
	global_load_dwordx4 v[120:123], v244, s[94:95] offset:640
	global_load_dwordx4 v[124:127], v245, s[94:95] offset:640
	global_load_dwordx4 v[128:131], v246, s[94:95] offset:640
	global_load_dwordx4 v[132:135], v247, s[94:95] offset:640
	global_load_dwordx4 v[136:139], v248, s[96:97] offset:1280
	global_load_dwordx4 v[140:143], v248, s[96:97] offset:1296
	global_load_dwordx4 v[144:147], v248, s[96:97] offset:3328
	global_load_dwordx4 v[148:151], v248, s[96:97] offset:3344
	global_load_dwordx4 v[212:215], v249, s[96:97] offset:1280
	global_load_dwordx4 v[216:219], v249, s[96:97] offset:1296
	global_load_dwordx4 v[220:223], v249, s[96:97] offset:3328
	global_load_dwordx4 v[224:227], v249, s[96:97] offset:3344
	global_load_dwordx4 v[228:231], v248, s[98:99] offset:1280
	global_load_dwordx4 v[232:235], v248, s[98:99] offset:1296
	s_waitcnt vmcnt(28)
	v_lshlrev_b32_e32 v236, 16, v64
	v_and_b32_e32 v237, 0xffff0000, v64
	v_lshlrev_b32_e32 v238, 16, v65
	v_and_b32_e32 v239, 0xffff0000, v65
	v_lshlrev_b32_e32 v240, 16, v66
	v_and_b32_e32 v241, 0xffff0000, v66
	v_lshlrev_b32_e32 v242, 16, v67
	v_and_b32_e32 v243, 0xffff0000, v67
	s_and_saveexec_b64 s[100:101], s[4:5]
	v_pk_fma_f32 v[114:115], v[82:83], v[238:239], v[114:115]
	v_pk_fma_f32 v[112:113], v[80:81], v[236:237], v[112:113]
	v_pk_fma_f32 v[118:119], v[86:87], v[242:243], v[118:119]
	v_pk_fma_f32 v[116:117], v[84:85], v[240:241], v[116:117]
	s_mov_b64 exec, s[100:101]
	v_lshlrev_b32_e32 v236, 16, v68
	v_and_b32_e32 v237, 0xffff0000, v68
	v_lshlrev_b32_e32 v238, 16, v69
	v_and_b32_e32 v239, 0xffff0000, v69
	v_lshlrev_b32_e32 v240, 16, v70
	v_and_b32_e32 v241, 0xffff0000, v70
	v_lshlrev_b32_e32 v242, 16, v71
	v_and_b32_e32 v243, 0xffff0000, v71
	s_and_saveexec_b64 s[100:101], s[6:7]
	v_pk_fma_f32 v[114:115], v[90:91], v[238:239], v[114:115]
	v_pk_fma_f32 v[112:113], v[88:89], v[236:237], v[112:113]
	v_pk_fma_f32 v[118:119], v[94:95], v[242:243], v[118:119]
	v_pk_fma_f32 v[116:117], v[92:93], v[240:241], v[116:117]
	s_mov_b64 exec, s[100:101]
	v_lshlrev_b32_e32 v236, 16, v72
	v_and_b32_e32 v237, 0xffff0000, v72
	v_lshlrev_b32_e32 v238, 16, v73
	v_and_b32_e32 v239, 0xffff0000, v73
	v_lshlrev_b32_e32 v240, 16, v74
	v_and_b32_e32 v241, 0xffff0000, v74
	v_lshlrev_b32_e32 v242, 16, v75
	v_and_b32_e32 v243, 0xffff0000, v75
	s_and_saveexec_b64 s[100:101], s[8:9]
	v_pk_fma_f32 v[114:115], v[98:99], v[238:239], v[114:115]
	v_pk_fma_f32 v[112:113], v[96:97], v[236:237], v[112:113]
	v_pk_fma_f32 v[118:119], v[102:103], v[242:243], v[118:119]
	v_pk_fma_f32 v[116:117], v[100:101], v[240:241], v[116:117]
	s_mov_b64 exec, s[100:101]
	v_lshlrev_b32_e32 v236, 16, v76
	v_and_b32_e32 v237, 0xffff0000, v76
	v_lshlrev_b32_e32 v238, 16, v77
	v_and_b32_e32 v239, 0xffff0000, v77
	v_lshlrev_b32_e32 v240, 16, v78
	v_and_b32_e32 v241, 0xffff0000, v78
	v_lshlrev_b32_e32 v242, 16, v79
	v_and_b32_e32 v243, 0xffff0000, v79
	v_pk_fma_f32 v[114:115], v[106:107], v[238:239], v[114:115]
	v_pk_fma_f32 v[112:113], v[104:105], v[236:237], v[112:113]
	v_pk_fma_f32 v[118:119], v[110:111], v[242:243], v[118:119]
	v_pk_fma_f32 v[116:117], v[108:109], v[240:241], v[116:117]
	v_cvt_pk_bf16_f32 v250, v112, v113
	v_cvt_pk_bf16_f32 v251, v114, v115
	v_cvt_pk_bf16_f32 v252, v116, v117
	v_cvt_pk_bf16_f32 v253, v118, v119
	ds_write_b128 v62, v[250:253] offset:384
	global_load_dwordx4 v[64:67], v244, s[94:95] offset:768
	global_load_dwordx4 v[68:71], v245, s[94:95] offset:768
	global_load_dwordx4 v[72:75], v246, s[94:95] offset:768
	global_load_dwordx4 v[76:79], v247, s[94:95] offset:768
	global_load_dwordx4 v[80:83], v248, s[96:97] offset:1536
	global_load_dwordx4 v[84:87], v248, s[96:97] offset:1552
	global_load_dwordx4 v[88:91], v248, s[96:97] offset:3584
	global_load_dwordx4 v[92:95], v248, s[96:97] offset:3600
	global_load_dwordx4 v[96:99], v249, s[96:97] offset:1536
	global_load_dwordx4 v[100:103], v249, s[96:97] offset:1552
	global_load_dwordx4 v[104:107], v249, s[96:97] offset:3584
	global_load_dwordx4 v[108:111], v249, s[96:97] offset:3600
	global_load_dwordx4 v[112:115], v248, s[98:99] offset:1536
	global_load_dwordx4 v[116:119], v248, s[98:99] offset:1552
	s_waitcnt vmcnt(28)
	v_lshlrev_b32_e32 v236, 16, v156
	v_and_b32_e32 v237, 0xffff0000, v156
	v_lshlrev_b32_e32 v238, 16, v157
	v_and_b32_e32 v239, 0xffff0000, v157
	v_lshlrev_b32_e32 v240, 16, v158
	v_and_b32_e32 v241, 0xffff0000, v158
	v_lshlrev_b32_e32 v242, 16, v159
	v_and_b32_e32 v243, 0xffff0000, v159
	s_and_saveexec_b64 s[100:101], s[4:5]
	v_pk_fma_f32 v[206:207], v[174:175], v[238:239], v[206:207]
	v_pk_fma_f32 v[204:205], v[172:173], v[236:237], v[204:205]
	v_pk_fma_f32 v[210:211], v[178:179], v[242:243], v[210:211]
	v_pk_fma_f32 v[208:209], v[176:177], v[240:241], v[208:209]
	s_mov_b64 exec, s[100:101]
	v_lshlrev_b32_e32 v236, 16, v160
	v_and_b32_e32 v237, 0xffff0000, v160
	v_lshlrev_b32_e32 v238, 16, v161
	v_and_b32_e32 v239, 0xffff0000, v161
	v_lshlrev_b32_e32 v240, 16, v162
	v_and_b32_e32 v241, 0xffff0000, v162
	v_lshlrev_b32_e32 v242, 16, v163
	v_and_b32_e32 v243, 0xffff0000, v163
	s_and_saveexec_b64 s[100:101], s[6:7]
	v_pk_fma_f32 v[206:207], v[182:183], v[238:239], v[206:207]
	v_pk_fma_f32 v[204:205], v[180:181], v[236:237], v[204:205]
	v_pk_fma_f32 v[210:211], v[186:187], v[242:243], v[210:211]
	v_pk_fma_f32 v[208:209], v[184:185], v[240:241], v[208:209]
	s_mov_b64 exec, s[100:101]
	v_lshlrev_b32_e32 v236, 16, v164
	v_and_b32_e32 v237, 0xffff0000, v164
	v_lshlrev_b32_e32 v238, 16, v165
	v_and_b32_e32 v239, 0xffff0000, v165
	v_lshlrev_b32_e32 v240, 16, v166
	v_and_b32_e32 v241, 0xffff0000, v166
	v_lshlrev_b32_e32 v242, 16, v167
	v_and_b32_e32 v243, 0xffff0000, v167
	s_and_saveexec_b64 s[100:101], s[8:9]
	v_pk_fma_f32 v[206:207], v[190:191], v[238:239], v[206:207]
	v_pk_fma_f32 v[204:205], v[188:189], v[236:237], v[204:205]
	v_pk_fma_f32 v[210:211], v[194:195], v[242:243], v[210:211]
	v_pk_fma_f32 v[208:209], v[192:193], v[240:241], v[208:209]
	s_mov_b64 exec, s[100:101]
	v_lshlrev_b32_e32 v236, 16, v168
	v_and_b32_e32 v237, 0xffff0000, v168
	v_lshlrev_b32_e32 v238, 16, v169
	v_and_b32_e32 v239, 0xffff0000, v169
	v_lshlrev_b32_e32 v240, 16, v170
	v_and_b32_e32 v241, 0xffff0000, v170
	v_lshlrev_b32_e32 v242, 16, v171
	v_and_b32_e32 v243, 0xffff0000, v171
	v_pk_fma_f32 v[206:207], v[198:199], v[238:239], v[206:207]
	v_pk_fma_f32 v[204:205], v[196:197], v[236:237], v[204:205]
	v_pk_fma_f32 v[210:211], v[202:203], v[242:243], v[210:211]
	v_pk_fma_f32 v[208:209], v[200:201], v[240:241], v[208:209]
	v_cvt_pk_bf16_f32 v250, v204, v205
	v_cvt_pk_bf16_f32 v251, v206, v207
	v_cvt_pk_bf16_f32 v252, v208, v209
	v_cvt_pk_bf16_f32 v253, v210, v211
	ds_write_b128 v62, v[250:253] offset:512
	global_load_dwordx4 v[156:159], v244, s[94:95] offset:896
	global_load_dwordx4 v[160:163], v245, s[94:95] offset:896
	global_load_dwordx4 v[164:167], v246, s[94:95] offset:896
	global_load_dwordx4 v[168:171], v247, s[94:95] offset:896
	global_load_dwordx4 v[172:175], v248, s[96:97] offset:1792
	global_load_dwordx4 v[176:179], v248, s[96:97] offset:1808
	global_load_dwordx4 v[180:183], v248, s[96:97] offset:3840
	global_load_dwordx4 v[184:187], v248, s[96:97] offset:3856
	global_load_dwordx4 v[188:191], v249, s[96:97] offset:1792
	global_load_dwordx4 v[192:195], v249, s[96:97] offset:1808
	global_load_dwordx4 v[196:199], v249, s[96:97] offset:3840
	global_load_dwordx4 v[200:203], v249, s[96:97] offset:3856
	global_load_dwordx4 v[204:207], v248, s[98:99] offset:1792
	global_load_dwordx4 v[208:211], v248, s[98:99] offset:1808
	s_waitcnt vmcnt(28)
	v_lshlrev_b32_e32 v236, 16, v120
	v_and_b32_e32 v237, 0xffff0000, v120
	v_lshlrev_b32_e32 v238, 16, v121
	v_and_b32_e32 v239, 0xffff0000, v121
	v_lshlrev_b32_e32 v240, 16, v122
	v_and_b32_e32 v241, 0xffff0000, v122
	v_lshlrev_b32_e32 v242, 16, v123
	v_and_b32_e32 v243, 0xffff0000, v123
	s_and_saveexec_b64 s[100:101], s[4:5]
	v_pk_fma_f32 v[230:231], v[138:139], v[238:239], v[230:231]
	v_pk_fma_f32 v[228:229], v[136:137], v[236:237], v[228:229]
	v_pk_fma_f32 v[234:235], v[142:143], v[242:243], v[234:235]
	v_pk_fma_f32 v[232:233], v[140:141], v[240:241], v[232:233]
	s_mov_b64 exec, s[100:101]
	v_lshlrev_b32_e32 v236, 16, v124
	v_and_b32_e32 v237, 0xffff0000, v124
	v_lshlrev_b32_e32 v238, 16, v125
	v_and_b32_e32 v239, 0xffff0000, v125
	v_lshlrev_b32_e32 v240, 16, v126
	v_and_b32_e32 v241, 0xffff0000, v126
	v_lshlrev_b32_e32 v242, 16, v127
	v_and_b32_e32 v243, 0xffff0000, v127
	s_and_saveexec_b64 s[100:101], s[6:7]
	v_pk_fma_f32 v[230:231], v[146:147], v[238:239], v[230:231]
	v_pk_fma_f32 v[228:229], v[144:145], v[236:237], v[228:229]
	v_pk_fma_f32 v[234:235], v[150:151], v[242:243], v[234:235]
	v_pk_fma_f32 v[232:233], v[148:149], v[240:241], v[232:233]
	s_mov_b64 exec, s[100:101]
	v_lshlrev_b32_e32 v236, 16, v128
	v_and_b32_e32 v237, 0xffff0000, v128
	v_lshlrev_b32_e32 v238, 16, v129
	v_and_b32_e32 v239, 0xffff0000, v129
	v_lshlrev_b32_e32 v240, 16, v130
	v_and_b32_e32 v241, 0xffff0000, v130
	v_lshlrev_b32_e32 v242, 16, v131
	v_and_b32_e32 v243, 0xffff0000, v131
	s_and_saveexec_b64 s[100:101], s[8:9]
	v_pk_fma_f32 v[230:231], v[214:215], v[238:239], v[230:231]
	v_pk_fma_f32 v[228:229], v[212:213], v[236:237], v[228:229]
	v_pk_fma_f32 v[234:235], v[218:219], v[242:243], v[234:235]
	v_pk_fma_f32 v[232:233], v[216:217], v[240:241], v[232:233]
	s_mov_b64 exec, s[100:101]
	v_lshlrev_b32_e32 v236, 16, v132
	v_and_b32_e32 v237, 0xffff0000, v132
	v_lshlrev_b32_e32 v238, 16, v133
	v_and_b32_e32 v239, 0xffff0000, v133
	v_lshlrev_b32_e32 v240, 16, v134
	v_and_b32_e32 v241, 0xffff0000, v134
	v_lshlrev_b32_e32 v242, 16, v135
	v_and_b32_e32 v243, 0xffff0000, v135
	v_pk_fma_f32 v[230:231], v[222:223], v[238:239], v[230:231]
	v_pk_fma_f32 v[228:229], v[220:221], v[236:237], v[228:229]
	v_pk_fma_f32 v[234:235], v[226:227], v[242:243], v[234:235]
	v_pk_fma_f32 v[232:233], v[224:225], v[240:241], v[232:233]
	v_cvt_pk_bf16_f32 v250, v228, v229
	v_cvt_pk_bf16_f32 v251, v230, v231
	v_cvt_pk_bf16_f32 v252, v232, v233
	v_cvt_pk_bf16_f32 v253, v234, v235
	ds_write_b128 v62, v[250:253] offset:640
	s_waitcnt vmcnt(14)
	v_lshlrev_b32_e32 v236, 16, v64
	v_and_b32_e32 v237, 0xffff0000, v64
	v_lshlrev_b32_e32 v238, 16, v65
	v_and_b32_e32 v239, 0xffff0000, v65
	v_lshlrev_b32_e32 v240, 16, v66
	v_and_b32_e32 v241, 0xffff0000, v66
	v_lshlrev_b32_e32 v242, 16, v67
	v_and_b32_e32 v243, 0xffff0000, v67
	s_and_saveexec_b64 s[100:101], s[4:5]
	v_pk_fma_f32 v[114:115], v[82:83], v[238:239], v[114:115]
	v_pk_fma_f32 v[112:113], v[80:81], v[236:237], v[112:113]
	v_pk_fma_f32 v[118:119], v[86:87], v[242:243], v[118:119]
	v_pk_fma_f32 v[116:117], v[84:85], v[240:241], v[116:117]
	s_mov_b64 exec, s[100:101]
	v_lshlrev_b32_e32 v236, 16, v68
	v_and_b32_e32 v237, 0xffff0000, v68
	v_lshlrev_b32_e32 v238, 16, v69
	v_and_b32_e32 v239, 0xffff0000, v69
	v_lshlrev_b32_e32 v240, 16, v70
	v_and_b32_e32 v241, 0xffff0000, v70
	v_lshlrev_b32_e32 v242, 16, v71
	v_and_b32_e32 v243, 0xffff0000, v71
	s_and_saveexec_b64 s[100:101], s[6:7]
	v_pk_fma_f32 v[114:115], v[90:91], v[238:239], v[114:115]
	v_pk_fma_f32 v[112:113], v[88:89], v[236:237], v[112:113]
	v_pk_fma_f32 v[118:119], v[94:95], v[242:243], v[118:119]
	v_pk_fma_f32 v[116:117], v[92:93], v[240:241], v[116:117]
	s_mov_b64 exec, s[100:101]
	v_lshlrev_b32_e32 v236, 16, v72
	v_and_b32_e32 v237, 0xffff0000, v72
	v_lshlrev_b32_e32 v238, 16, v73
	v_and_b32_e32 v239, 0xffff0000, v73
	v_lshlrev_b32_e32 v240, 16, v74
	v_and_b32_e32 v241, 0xffff0000, v74
	v_lshlrev_b32_e32 v242, 16, v75
	v_and_b32_e32 v243, 0xffff0000, v75
	s_and_saveexec_b64 s[100:101], s[8:9]
	v_pk_fma_f32 v[114:115], v[98:99], v[238:239], v[114:115]
	v_pk_fma_f32 v[112:113], v[96:97], v[236:237], v[112:113]
	v_pk_fma_f32 v[118:119], v[102:103], v[242:243], v[118:119]
	v_pk_fma_f32 v[116:117], v[100:101], v[240:241], v[116:117]
	s_mov_b64 exec, s[100:101]
	v_lshlrev_b32_e32 v236, 16, v76
	v_and_b32_e32 v237, 0xffff0000, v76
	v_lshlrev_b32_e32 v238, 16, v77
	v_and_b32_e32 v239, 0xffff0000, v77
	v_lshlrev_b32_e32 v240, 16, v78
	v_and_b32_e32 v241, 0xffff0000, v78
	v_lshlrev_b32_e32 v242, 16, v79
	v_and_b32_e32 v243, 0xffff0000, v79
	v_pk_fma_f32 v[114:115], v[106:107], v[238:239], v[114:115]
	v_pk_fma_f32 v[112:113], v[104:105], v[236:237], v[112:113]
	v_pk_fma_f32 v[118:119], v[110:111], v[242:243], v[118:119]
	v_pk_fma_f32 v[116:117], v[108:109], v[240:241], v[116:117]
	v_cvt_pk_bf16_f32 v250, v112, v113
	v_cvt_pk_bf16_f32 v251, v114, v115
	v_cvt_pk_bf16_f32 v252, v116, v117
	v_cvt_pk_bf16_f32 v253, v118, v119
	ds_write_b128 v62, v[250:253] offset:768
	s_waitcnt vmcnt(0)
	v_lshlrev_b32_e32 v236, 16, v156
	v_and_b32_e32 v237, 0xffff0000, v156
	v_lshlrev_b32_e32 v238, 16, v157
	v_and_b32_e32 v239, 0xffff0000, v157
	v_lshlrev_b32_e32 v240, 16, v158
	v_and_b32_e32 v241, 0xffff0000, v158
	v_lshlrev_b32_e32 v242, 16, v159
	v_and_b32_e32 v243, 0xffff0000, v159
	s_and_saveexec_b64 s[100:101], s[4:5]
	v_pk_fma_f32 v[206:207], v[174:175], v[238:239], v[206:207]
	v_pk_fma_f32 v[204:205], v[172:173], v[236:237], v[204:205]
	v_pk_fma_f32 v[210:211], v[178:179], v[242:243], v[210:211]
	v_pk_fma_f32 v[208:209], v[176:177], v[240:241], v[208:209]
	s_mov_b64 exec, s[100:101]
	v_lshlrev_b32_e32 v236, 16, v160
	v_and_b32_e32 v237, 0xffff0000, v160
	v_lshlrev_b32_e32 v238, 16, v161
	v_and_b32_e32 v239, 0xffff0000, v161
	v_lshlrev_b32_e32 v240, 16, v162
	v_and_b32_e32 v241, 0xffff0000, v162
	v_lshlrev_b32_e32 v242, 16, v163
	v_and_b32_e32 v243, 0xffff0000, v163
	s_and_saveexec_b64 s[100:101], s[6:7]
	v_pk_fma_f32 v[206:207], v[182:183], v[238:239], v[206:207]
	v_pk_fma_f32 v[204:205], v[180:181], v[236:237], v[204:205]
	v_pk_fma_f32 v[210:211], v[186:187], v[242:243], v[210:211]
	v_pk_fma_f32 v[208:209], v[184:185], v[240:241], v[208:209]
	s_mov_b64 exec, s[100:101]
	v_lshlrev_b32_e32 v236, 16, v164
	v_and_b32_e32 v237, 0xffff0000, v164
	v_lshlrev_b32_e32 v238, 16, v165
	v_and_b32_e32 v239, 0xffff0000, v165
	v_lshlrev_b32_e32 v240, 16, v166
	v_and_b32_e32 v241, 0xffff0000, v166
	v_lshlrev_b32_e32 v242, 16, v167
	v_and_b32_e32 v243, 0xffff0000, v167
	s_and_saveexec_b64 s[100:101], s[8:9]
	v_pk_fma_f32 v[206:207], v[190:191], v[238:239], v[206:207]
	v_pk_fma_f32 v[204:205], v[188:189], v[236:237], v[204:205]
	v_pk_fma_f32 v[210:211], v[194:195], v[242:243], v[210:211]
	v_pk_fma_f32 v[208:209], v[192:193], v[240:241], v[208:209]
	s_mov_b64 exec, s[100:101]
	v_lshlrev_b32_e32 v236, 16, v168
	v_and_b32_e32 v237, 0xffff0000, v168
	v_lshlrev_b32_e32 v238, 16, v169
	v_and_b32_e32 v239, 0xffff0000, v169
	v_lshlrev_b32_e32 v240, 16, v170
	v_and_b32_e32 v241, 0xffff0000, v170
	v_lshlrev_b32_e32 v242, 16, v171
	v_and_b32_e32 v243, 0xffff0000, v171
	v_pk_fma_f32 v[206:207], v[198:199], v[238:239], v[206:207]
	v_pk_fma_f32 v[204:205], v[196:197], v[236:237], v[204:205]
	v_pk_fma_f32 v[210:211], v[202:203], v[242:243], v[210:211]
	v_pk_fma_f32 v[208:209], v[200:201], v[240:241], v[208:209]
	v_cvt_pk_bf16_f32 v250, v204, v205
	v_cvt_pk_bf16_f32 v251, v206, v207
	v_cvt_pk_bf16_f32 v252, v208, v209
	v_cvt_pk_bf16_f32 v253, v210, v211
	ds_write_b128 v62, v[250:253] offset:896
